# plus out-projection epilogue: both column halves' residual loads of a row group issued together
# baseline (speedup 1.0000x reference)
; DI u32x4 pack8(const float (&v)[8]) { u32x4 w; w.x = pk2(v[0], v[1]); w.y = pk2(v[2], v[3]); w.z = pk2(v[4], v[5]); w.w = pk2(v[6], v[7]); return w; }
;     DI void operator()(const f32x4 (&acc)[2][2][4][2], const pg8::Unit& u, int wr, int wc, int fr, int fq) const {
;     ...
;             for (int m = 0; m < 4; ++m) { const int row = row0 + ai * 128 + m * 16; const size_t off = (size_t)row * DMODEL + col0; float s = 0.f, q = 0.f;
; #pragma unroll
;                 for (int bj = 0; bj < 2; ++bj) { float r[8];
;                     if (res32) { const f32x4 r0 = *(const f32x4*)(res32 + off + bj * 128), r1 = *(const f32x4*)(res32 + off + bj * 128 + 4); r[0] = r0[0]; r[1] = r0[1]; r[2] = r0[2]; r[3] = r0[3]; r[4] = r1[0]; r[5] = r1[1]; r[6] = r1[2]; r[7] = r1[3]; }
;                     else unpack8(*(const u32x4*)(res16 + off + bj * 128), r);
;                     float o[8];
; #pragma unroll
;                     for (int k = 0; k < 8; ++k) { o[k] = r[k] * ALPHA + acc[ai][bj][m][k >> 2][k & 3]; s += o[k]; q += o[k] * o[k]; }
;                     *(u32x4*)(XBo + off + bj * 128) = pack8(o); }
.LBB0_1746:
	s_lshl_b32 s2, s18, 8
	v_mov_b32_e32 v163, v158
	v_mov_b32_e32 v162, v159
	s_add_i32 s2, s2, s58
	s_andn2_b64 vcc, exec, s[38:39]
	v_add_u32_e32 v150, s2, v163
	s_lshl_b32 s2, s90, 8
	s_or_b32 s2, s2, s82
	v_lshl_add_u32 v148, v162, 3, s2
	v_ashrrev_i32_e32 v151, 31, v150
	v_ashrrev_i32_e32 v149, 31, v148
	v_lshlrev_b64 v[130:131], 10, v[150:151]
	v_lshl_add_u64 v[152:153], v[130:131], 0, v[148:149]
	v_cndmask_b32_e64 v130, 0, 1, s[38:39]
	v_cmp_ne_u32_e64 s[18:19], 1, v130
	v_lshl_add_u64 v[154:155], v[152:153], 2, s[26:27]
	s_cbranch_vccnz .LBB0_1748
	global_load_dwordx4 v[134:137], v[154:155], off
	global_load_dwordx4 v[130:133], v[154:155], off offset:16
	global_load_dwordx4 v[164:167], v[154:155], off offset:528
	global_load_dwordx4 v[168:171], v[154:155], off offset:512
	s_mov_b64 s[2:3], 0
	s_branch .LBB0_1749

; DI u32x4 pack8(const float (&v)[8]) { u32x4 w; w.x = pk2(v[0], v[1]); w.y = pk2(v[2], v[3]); w.z = pk2(v[4], v[5]); w.w = pk2(v[6], v[7]); return w; }
;     DI void operator()(const f32x4 (&acc)[2][2][4][2], const pg8::Unit& u, int wr, int wc, int fr, int fq) const {
;     ...
;                 for (int bj = 0; bj < 2; ++bj) { float r[8];
;                     if (res32) { const f32x4 r0 = *(const f32x4*)(res32 + off + bj * 128), r1 = *(const f32x4*)(res32 + off + bj * 128 + 4); r[0] = r0[0]; r[1] = r0[1]; r[2] = r0[2]; r[3] = r0[3]; r[4] = r1[0]; r[5] = r1[1]; r[6] = r1[2]; r[7] = r1[3]; }
;                     else unpack8(*(const u32x4*)(res16 + off + bj * 128), r);
;                     float o[8];
; #pragma unroll
;                     for (int k = 0; k < 8; ++k) { o[k] = r[k] * ALPHA + acc[ai][bj][m][k >> 2][k & 3]; s += o[k]; q += o[k] * o[k]; }
;                     *(u32x4*)(XBo + off + bj * 128) = pack8(o); }
.LBB0_1749:
	s_andn2_b64 vcc, exec, s[2:3]
	v_lshl_add_u64 v[152:153], v[152:153], 1, s[24:25]
	v_readlane_b32 s61, v254, 55
	s_cbranch_vccnz .LBB0_1751
	global_load_dwordx4 v[130:133], v[152:153], off
	global_load_dwordx4 v[172:175], v[152:153], off offset:256
	s_waitcnt vmcnt(0)
	v_lshlrev_b32_e32 v134, 16, v130
	v_and_b32_e32 v135, 0xffff0000, v130
	v_lshlrev_b32_e32 v136, 16, v131
	v_and_b32_e32 v137, 0xffff0000, v131
	v_lshlrev_b32_e32 v130, 16, v132
	v_and_b32_e32 v131, 0xffff0000, v132
	v_lshlrev_b32_e32 v132, 16, v133
	v_and_b32_e32 v133, 0xffff0000, v133
.LBB0_1751:
	s_waitcnt vmcnt(0)
	v_pk_fma_f32 v[134:135], v[134:135], s[86:87], v[126:127] op_sel_hi:[1,0,1]
	v_pk_fma_f32 v[136:137], v[136:137], s[86:87], v[128:129] op_sel_hi:[1,0,1]
	v_pk_fma_f32 v[156:157], v[130:131], s[86:87], v[122:123] op_sel_hi:[1,0,1]
	v_pk_fma_f32 v[132:133], v[132:133], s[86:87], v[124:125] op_sel_hi:[1,0,1]
	v_cvt_pk_bf16_f32 v122, v134, v135
	v_cvt_pk_bf16_f32 v123, v136, v137
	v_cvt_pk_bf16_f32 v124, v156, v157
	v_cvt_pk_bf16_f32 v125, v132, v133
	s_and_b64 vcc, exec, s[18:19]
	global_store_dwordx4 v[152:153], v[122:125], off
	s_cbranch_vccnz .LBB0_1815
	s_nop 2
	v_mov_b32_e32 v122, v164
	v_mov_b32_e32 v123, v165
	v_mov_b32_e32 v124, v166
	v_mov_b32_e32 v125, v167
	v_mov_b32_e32 v126, v168
	v_mov_b32_e32 v127, v169
	v_mov_b32_e32 v128, v170
	v_mov_b32_e32 v129, v171
	s_waitcnt vmcnt(1)
	v_mov_b32_e32 v130, v125
	s_cbranch_execnz .LBB0_1754
.LBB0_1753:
	s_nop 2
	v_mov_b32_e32 v122, v172
	v_mov_b32_e32 v123, v173
	v_mov_b32_e32 v124, v174
	v_mov_b32_e32 v125, v175
	s_waitcnt vmcnt(0)
	v_lshlrev_b32_e32 v126, 16, v122
	v_and_b32_e32 v127, 0xffff0000, v122
	v_lshlrev_b32_e32 v128, 16, v123
	v_and_b32_e32 v129, 0xffff0000, v123
	v_lshlrev_b32_e32 v122, 16, v124
	v_and_b32_e32 v123, 0xffff0000, v124
	v_lshlrev_b32_e32 v124, 16, v125
	v_and_b32_e32 v130, 0xffff0000, v125

; DI u32x4 pack8(const float (&v)[8]) { u32x4 w; w.x = pk2(v[0], v[1]); w.y = pk2(v[2], v[3]); w.z = pk2(v[4], v[5]); w.w = pk2(v[6], v[7]); return w; }
;     DI void operator()(const f32x4 (&acc)[2][2][4][2], const pg8::Unit& u, int wr, int wc, int fr, int fq) const {
;     ...
;             for (int m = 0; m < 4; ++m) { const int row = row0 + ai * 128 + m * 16; const size_t off = (size_t)row * DMODEL + col0; float s = 0.f, q = 0.f;
; #pragma unroll
;                 for (int bj = 0; bj < 2; ++bj) { float r[8];
;                     if (res32) { const f32x4 r0 = *(const f32x4*)(res32 + off + bj * 128), r1 = *(const f32x4*)(res32 + off + bj * 128 + 4); r[0] = r0[0]; r[1] = r0[1]; r[2] = r0[2]; r[3] = r0[3]; r[4] = r1[0]; r[5] = r1[1]; r[6] = r1[2]; r[7] = r1[3]; }
;                     else unpack8(*(const u32x4*)(res16 + off + bj * 128), r);
;                     float o[8];
; #pragma unroll
;                     for (int k = 0; k < 8; ++k) { o[k] = r[k] * ALPHA + acc[ai][bj][m][k >> 2][k & 3]; s += o[k]; q += o[k] * o[k]; }
;                     *(u32x4*)(XBo + off + bj * 128) = pack8(o); }
.LBB0_1756:
	s_or_b64 exec, exec, s[2:3]
	v_add_u32_e32 v122, 16, v150
	v_ashrrev_i32_e32 v123, 31, v122
	v_lshlrev_b64 v[114:115], 10, v[122:123]
	v_lshl_add_u64 v[124:125], v[114:115], 0, v[148:149]
	s_and_b64 vcc, exec, s[18:19]
	v_lshl_add_u64 v[126:127], v[124:125], 2, s[26:27]
	s_cbranch_vccnz .LBB0_1816
	global_load_dwordx4 v[118:121], v[126:127], off
	s_waitcnt lgkmcnt(0)
	global_load_dwordx4 v[114:117], v[126:127], off offset:16
	global_load_dwordx4 v[164:167], v[126:127], off offset:528
	global_load_dwordx4 v[168:171], v[126:127], off offset:512
	v_lshl_add_u64 v[124:125], v[124:125], 1, s[24:25]
	s_cbranch_execnz .LBB0_1759
.LBB0_1758:
	s_waitcnt lgkmcnt(0)
	global_load_dwordx4 v[114:117], v[124:125], off
	global_load_dwordx4 v[172:175], v[124:125], off offset:256
	s_waitcnt vmcnt(0)
	v_lshlrev_b32_e32 v118, 16, v114
	v_and_b32_e32 v119, 0xffff0000, v114
	v_lshlrev_b32_e32 v120, 16, v115
	v_and_b32_e32 v121, 0xffff0000, v115
	v_lshlrev_b32_e32 v114, 16, v116
	v_and_b32_e32 v115, 0xffff0000, v116
	v_lshlrev_b32_e32 v116, 16, v117
	v_and_b32_e32 v117, 0xffff0000, v117
.LBB0_1759:
	s_waitcnt vmcnt(1)
	v_pk_fma_f32 v[118:119], v[118:119], s[86:87], v[110:111] op_sel_hi:[1,0,1]
	v_pk_fma_f32 v[120:121], v[120:121], s[86:87], v[112:113] op_sel_hi:[1,0,1]
	s_waitcnt vmcnt(0)
	v_pk_fma_f32 v[128:129], v[114:115], s[86:87], v[106:107] op_sel_hi:[1,0,1]
	s_waitcnt lgkmcnt(0)
	v_pk_fma_f32 v[116:117], v[116:117], s[86:87], v[108:109] op_sel_hi:[1,0,1]
	v_cvt_pk_bf16_f32 v106, v118, v119
	v_cvt_pk_bf16_f32 v107, v120, v121
	v_cvt_pk_bf16_f32 v108, v128, v129
	v_cvt_pk_bf16_f32 v109, v116, v117
	s_and_b64 vcc, exec, s[18:19]
	global_store_dwordx4 v[124:125], v[106:109], off
	s_cbranch_vccnz .LBB0_1817
	s_nop 2
	v_mov_b32_e32 v106, v164
	v_mov_b32_e32 v107, v165
	v_mov_b32_e32 v108, v166
	v_mov_b32_e32 v109, v167
	v_mov_b32_e32 v110, v168
	v_mov_b32_e32 v111, v169
	v_mov_b32_e32 v112, v170
	v_mov_b32_e32 v113, v171
	s_waitcnt vmcnt(1)
	v_mov_b32_e32 v114, v109
	s_cbranch_execnz .LBB0_1762
.LBB0_1761:
	s_nop 2
	v_mov_b32_e32 v106, v172
	v_mov_b32_e32 v107, v173
	v_mov_b32_e32 v108, v174
	v_mov_b32_e32 v109, v175
	s_waitcnt vmcnt(0)
	v_lshlrev_b32_e32 v110, 16, v106
	v_and_b32_e32 v111, 0xffff0000, v106
	v_lshlrev_b32_e32 v112, 16, v107
	v_and_b32_e32 v113, 0xffff0000, v107
	v_lshlrev_b32_e32 v106, 16, v108
	v_and_b32_e32 v107, 0xffff0000, v108
	v_lshlrev_b32_e32 v108, 16, v109
	v_and_b32_e32 v114, 0xffff0000, v109

; DI u32x4 pack8(const float (&v)[8]) { u32x4 w; w.x = pk2(v[0], v[1]); w.y = pk2(v[2], v[3]); w.z = pk2(v[4], v[5]); w.w = pk2(v[6], v[7]); return w; }
;     DI void operator()(const f32x4 (&acc)[2][2][4][2], const pg8::Unit& u, int wr, int wc, int fr, int fq) const {
;     ...
;             for (int m = 0; m < 4; ++m) { const int row = row0 + ai * 128 + m * 16; const size_t off = (size_t)row * DMODEL + col0; float s = 0.f, q = 0.f;
; #pragma unroll
;                 for (int bj = 0; bj < 2; ++bj) { float r[8];
;                     if (res32) { const f32x4 r0 = *(const f32x4*)(res32 + off + bj * 128), r1 = *(const f32x4*)(res32 + off + bj * 128 + 4); r[0] = r0[0]; r[1] = r0[1]; r[2] = r0[2]; r[3] = r0[3]; r[4] = r1[0]; r[5] = r1[1]; r[6] = r1[2]; r[7] = r1[3]; }
;                     else unpack8(*(const u32x4*)(res16 + off + bj * 128), r);
;                     float o[8];
; #pragma unroll
;                     for (int k = 0; k < 8; ++k) { o[k] = r[k] * ALPHA + acc[ai][bj][m][k >> 2][k & 3]; s += o[k]; q += o[k] * o[k]; }
;                     *(u32x4*)(XBo + off + bj * 128) = pack8(o); }
.LBB0_1764:
	s_or_b64 exec, exec, s[2:3]
	v_add_u32_e32 v106, 32, v150
	v_ashrrev_i32_e32 v107, 31, v106
	v_lshlrev_b64 v[98:99], 10, v[106:107]
	v_lshl_add_u64 v[108:109], v[98:99], 0, v[148:149]
	s_and_b64 vcc, exec, s[18:19]
	v_lshl_add_u64 v[110:111], v[108:109], 2, s[26:27]
	s_cbranch_vccnz .LBB0_1818
	global_load_dwordx4 v[102:105], v[110:111], off
	s_waitcnt lgkmcnt(0)
	global_load_dwordx4 v[98:101], v[110:111], off offset:16
	global_load_dwordx4 v[164:167], v[110:111], off offset:528
	global_load_dwordx4 v[168:171], v[110:111], off offset:512
	v_lshl_add_u64 v[108:109], v[108:109], 1, s[24:25]
	s_cbranch_execnz .LBB0_1767
.LBB0_1766:
	s_waitcnt lgkmcnt(0)
	global_load_dwordx4 v[98:101], v[108:109], off
	global_load_dwordx4 v[172:175], v[108:109], off offset:256
	s_waitcnt vmcnt(0)
	v_lshlrev_b32_e32 v102, 16, v98
	v_and_b32_e32 v103, 0xffff0000, v98
	v_lshlrev_b32_e32 v104, 16, v99
	v_and_b32_e32 v105, 0xffff0000, v99
	v_lshlrev_b32_e32 v98, 16, v100
	v_and_b32_e32 v99, 0xffff0000, v100
	v_lshlrev_b32_e32 v100, 16, v101
	v_and_b32_e32 v101, 0xffff0000, v101
.LBB0_1767:
	s_waitcnt vmcnt(1)
	v_pk_fma_f32 v[102:103], v[102:103], s[86:87], v[94:95] op_sel_hi:[1,0,1]
	v_pk_fma_f32 v[104:105], v[104:105], s[86:87], v[96:97] op_sel_hi:[1,0,1]
	s_waitcnt vmcnt(0)
	v_pk_fma_f32 v[112:113], v[98:99], s[86:87], v[90:91] op_sel_hi:[1,0,1]
	s_waitcnt lgkmcnt(0)
	v_pk_fma_f32 v[100:101], v[100:101], s[86:87], v[92:93] op_sel_hi:[1,0,1]
	v_cvt_pk_bf16_f32 v90, v102, v103
	v_cvt_pk_bf16_f32 v91, v104, v105
	v_cvt_pk_bf16_f32 v92, v112, v113
	v_cvt_pk_bf16_f32 v93, v100, v101
	s_and_b64 vcc, exec, s[18:19]
	global_store_dwordx4 v[108:109], v[90:93], off
	s_cbranch_vccnz .LBB0_1819
	s_nop 2
	v_mov_b32_e32 v90, v164
	v_mov_b32_e32 v91, v165
	v_mov_b32_e32 v92, v166
	v_mov_b32_e32 v93, v167
	v_mov_b32_e32 v94, v168
	v_mov_b32_e32 v95, v169
	v_mov_b32_e32 v96, v170
	v_mov_b32_e32 v97, v171
	s_waitcnt vmcnt(1)
	v_mov_b32_e32 v98, v93
	s_cbranch_execnz .LBB0_1770
.LBB0_1769:
	s_nop 2
	v_mov_b32_e32 v90, v172
	v_mov_b32_e32 v91, v173
	v_mov_b32_e32 v92, v174
	v_mov_b32_e32 v93, v175
	s_waitcnt vmcnt(0)
	v_lshlrev_b32_e32 v94, 16, v90
	v_and_b32_e32 v95, 0xffff0000, v90
	v_lshlrev_b32_e32 v96, 16, v91
	v_and_b32_e32 v97, 0xffff0000, v91
	v_lshlrev_b32_e32 v90, 16, v92
	v_and_b32_e32 v91, 0xffff0000, v92
	v_lshlrev_b32_e32 v92, 16, v93
	v_and_b32_e32 v98, 0xffff0000, v93

; DI u32x4 pack8(const float (&v)[8]) { u32x4 w; w.x = pk2(v[0], v[1]); w.y = pk2(v[2], v[3]); w.z = pk2(v[4], v[5]); w.w = pk2(v[6], v[7]); return w; }
;     DI void operator()(const f32x4 (&acc)[2][2][4][2], const pg8::Unit& u, int wr, int wc, int fr, int fq) const {
;     ...
;             for (int m = 0; m < 4; ++m) { const int row = row0 + ai * 128 + m * 16; const size_t off = (size_t)row * DMODEL + col0; float s = 0.f, q = 0.f;
; #pragma unroll
;                 for (int bj = 0; bj < 2; ++bj) { float r[8];
;                     if (res32) { const f32x4 r0 = *(const f32x4*)(res32 + off + bj * 128), r1 = *(const f32x4*)(res32 + off + bj * 128 + 4); r[0] = r0[0]; r[1] = r0[1]; r[2] = r0[2]; r[3] = r0[3]; r[4] = r1[0]; r[5] = r1[1]; r[6] = r1[2]; r[7] = r1[3]; }
;                     else unpack8(*(const u32x4*)(res16 + off + bj * 128), r);
;                     float o[8];
; #pragma unroll
;                     for (int k = 0; k < 8; ++k) { o[k] = r[k] * ALPHA + acc[ai][bj][m][k >> 2][k & 3]; s += o[k]; q += o[k] * o[k]; }
;                     *(u32x4*)(XBo + off + bj * 128) = pack8(o); }
.LBB0_1772:
	s_or_b64 exec, exec, s[2:3]
	v_add_u32_e32 v90, 48, v150
	v_ashrrev_i32_e32 v91, 31, v90
	v_lshlrev_b64 v[82:83], 10, v[90:91]
	v_lshl_add_u64 v[92:93], v[82:83], 0, v[148:149]
	s_and_b64 vcc, exec, s[18:19]
	v_lshl_add_u64 v[94:95], v[92:93], 2, s[26:27]
	s_cbranch_vccnz .LBB0_1820
	global_load_dwordx4 v[86:89], v[94:95], off
	s_waitcnt lgkmcnt(0)
	global_load_dwordx4 v[82:85], v[94:95], off offset:16
	global_load_dwordx4 v[164:167], v[94:95], off offset:528
	global_load_dwordx4 v[168:171], v[94:95], off offset:512
	v_lshl_add_u64 v[92:93], v[92:93], 1, s[24:25]
	s_cbranch_execnz .LBB0_1775
.LBB0_1774:
	s_waitcnt lgkmcnt(0)
	global_load_dwordx4 v[82:85], v[92:93], off
	global_load_dwordx4 v[172:175], v[92:93], off offset:256
	s_waitcnt vmcnt(0)
	v_lshlrev_b32_e32 v86, 16, v82
	v_and_b32_e32 v87, 0xffff0000, v82
	v_lshlrev_b32_e32 v88, 16, v83
	v_and_b32_e32 v89, 0xffff0000, v83
	v_lshlrev_b32_e32 v82, 16, v84
	v_and_b32_e32 v83, 0xffff0000, v84
	v_lshlrev_b32_e32 v84, 16, v85
	v_and_b32_e32 v85, 0xffff0000, v85
.LBB0_1775:
	s_waitcnt vmcnt(1)
	v_pk_fma_f32 v[86:87], v[86:87], s[86:87], v[78:79] op_sel_hi:[1,0,1]
	v_pk_fma_f32 v[88:89], v[88:89], s[86:87], v[80:81] op_sel_hi:[1,0,1]
	s_waitcnt vmcnt(0)
	v_pk_fma_f32 v[96:97], v[82:83], s[86:87], v[74:75] op_sel_hi:[1,0,1]
	s_waitcnt lgkmcnt(0)
	v_pk_fma_f32 v[84:85], v[84:85], s[86:87], v[76:77] op_sel_hi:[1,0,1]
	v_cvt_pk_bf16_f32 v74, v86, v87
	v_cvt_pk_bf16_f32 v75, v88, v89
	v_cvt_pk_bf16_f32 v76, v96, v97
	v_cvt_pk_bf16_f32 v77, v84, v85
	s_and_b64 vcc, exec, s[18:19]
	global_store_dwordx4 v[92:93], v[74:77], off
	s_cbranch_vccnz .LBB0_1821
	s_nop 2
	v_mov_b32_e32 v74, v164
	v_mov_b32_e32 v75, v165
	v_mov_b32_e32 v76, v166
	v_mov_b32_e32 v77, v167
	v_mov_b32_e32 v78, v168
	v_mov_b32_e32 v79, v169
	v_mov_b32_e32 v80, v170
	v_mov_b32_e32 v81, v171
	s_waitcnt vmcnt(1)
	v_mov_b32_e32 v82, v77
	s_cbranch_execnz .LBB0_1778
.LBB0_1777:
	s_nop 2
	v_mov_b32_e32 v74, v172
	v_mov_b32_e32 v75, v173
	v_mov_b32_e32 v76, v174
	v_mov_b32_e32 v77, v175
	s_waitcnt vmcnt(0)
	v_lshlrev_b32_e32 v78, 16, v74
	v_and_b32_e32 v79, 0xffff0000, v74
	v_lshlrev_b32_e32 v80, 16, v75
	v_and_b32_e32 v81, 0xffff0000, v75
	v_lshlrev_b32_e32 v74, 16, v76
	v_and_b32_e32 v75, 0xffff0000, v76
	v_lshlrev_b32_e32 v76, 16, v77
	v_and_b32_e32 v82, 0xffff0000, v77

; DI u32x4 pack8(const float (&v)[8]) { u32x4 w; w.x = pk2(v[0], v[1]); w.y = pk2(v[2], v[3]); w.z = pk2(v[4], v[5]); w.w = pk2(v[6], v[7]); return w; }
;     DI void operator()(const f32x4 (&acc)[2][2][4][2], const pg8::Unit& u, int wr, int wc, int fr, int fq) const {
;     ...
;             for (int m = 0; m < 4; ++m) { const int row = row0 + ai * 128 + m * 16; const size_t off = (size_t)row * DMODEL + col0; float s = 0.f, q = 0.f;
; #pragma unroll
;                 for (int bj = 0; bj < 2; ++bj) { float r[8];
;                     if (res32) { const f32x4 r0 = *(const f32x4*)(res32 + off + bj * 128), r1 = *(const f32x4*)(res32 + off + bj * 128 + 4); r[0] = r0[0]; r[1] = r0[1]; r[2] = r0[2]; r[3] = r0[3]; r[4] = r1[0]; r[5] = r1[1]; r[6] = r1[2]; r[7] = r1[3]; }
;                     else unpack8(*(const u32x4*)(res16 + off + bj * 128), r);
;                     float o[8];
; #pragma unroll
;                     for (int k = 0; k < 8; ++k) { o[k] = r[k] * ALPHA + acc[ai][bj][m][k >> 2][k & 3]; s += o[k]; q += o[k] * o[k]; }
;                     *(u32x4*)(XBo + off + bj * 128) = pack8(o); }
.LBB0_1780:
	s_or_b64 exec, exec, s[2:3]
	v_add_u32_e32 v74, 0x80, v150
	v_ashrrev_i32_e32 v75, 31, v74
	v_lshlrev_b64 v[66:67], 10, v[74:75]
	v_lshl_add_u64 v[76:77], v[66:67], 0, v[148:149]
	s_and_b64 vcc, exec, s[18:19]
	v_lshl_add_u64 v[78:79], v[76:77], 2, s[26:27]
	s_cbranch_vccnz .LBB0_1822
	global_load_dwordx4 v[70:73], v[78:79], off
	s_waitcnt lgkmcnt(0)
	global_load_dwordx4 v[66:69], v[78:79], off offset:16
	global_load_dwordx4 v[164:167], v[78:79], off offset:528
	global_load_dwordx4 v[168:171], v[78:79], off offset:512
	v_lshl_add_u64 v[76:77], v[76:77], 1, s[24:25]
	s_cbranch_execnz .LBB0_1783
.LBB0_1782:
	s_waitcnt lgkmcnt(0)
	global_load_dwordx4 v[66:69], v[76:77], off
	global_load_dwordx4 v[172:175], v[76:77], off offset:256
	s_waitcnt vmcnt(0)
	v_lshlrev_b32_e32 v70, 16, v66
	v_and_b32_e32 v71, 0xffff0000, v66
	v_lshlrev_b32_e32 v72, 16, v67
	v_and_b32_e32 v73, 0xffff0000, v67
	v_lshlrev_b32_e32 v66, 16, v68
	v_and_b32_e32 v67, 0xffff0000, v68
	v_lshlrev_b32_e32 v68, 16, v69
	v_and_b32_e32 v69, 0xffff0000, v69
.LBB0_1783:
	s_waitcnt vmcnt(1)
	v_pk_fma_f32 v[70:71], v[70:71], s[86:87], v[62:63] op_sel_hi:[1,0,1]
	v_pk_fma_f32 v[72:73], v[72:73], s[86:87], v[64:65] op_sel_hi:[1,0,1]
	s_waitcnt vmcnt(0)
	v_pk_fma_f32 v[80:81], v[66:67], s[86:87], v[58:59] op_sel_hi:[1,0,1]
	s_waitcnt lgkmcnt(0)
	v_pk_fma_f32 v[68:69], v[68:69], s[86:87], v[60:61] op_sel_hi:[1,0,1]
	v_cvt_pk_bf16_f32 v58, v70, v71
	v_cvt_pk_bf16_f32 v59, v72, v73
	v_cvt_pk_bf16_f32 v60, v80, v81
	v_cvt_pk_bf16_f32 v61, v68, v69
	s_and_b64 vcc, exec, s[18:19]
	global_store_dwordx4 v[76:77], v[58:61], off
	s_cbranch_vccnz .LBB0_1823
	s_nop 2
	v_mov_b32_e32 v58, v164
	v_mov_b32_e32 v59, v165
	v_mov_b32_e32 v60, v166
	v_mov_b32_e32 v61, v167
	v_mov_b32_e32 v62, v168
	v_mov_b32_e32 v63, v169
	v_mov_b32_e32 v64, v170
	v_mov_b32_e32 v65, v171
	s_waitcnt vmcnt(1)
	v_mov_b32_e32 v66, v61
	s_cbranch_execnz .LBB0_1786
.LBB0_1785:
	s_nop 2
	v_mov_b32_e32 v58, v172
	v_mov_b32_e32 v59, v173
	v_mov_b32_e32 v60, v174
	v_mov_b32_e32 v61, v175
	s_waitcnt vmcnt(0)
	v_lshlrev_b32_e32 v62, 16, v58
	v_and_b32_e32 v63, 0xffff0000, v58
	v_lshlrev_b32_e32 v64, 16, v59
	v_and_b32_e32 v65, 0xffff0000, v59
	v_lshlrev_b32_e32 v58, 16, v60
	v_and_b32_e32 v59, 0xffff0000, v60
	v_lshlrev_b32_e32 v60, 16, v61
	v_and_b32_e32 v66, 0xffff0000, v61

; DI u32x4 pack8(const float (&v)[8]) { u32x4 w; w.x = pk2(v[0], v[1]); w.y = pk2(v[2], v[3]); w.z = pk2(v[4], v[5]); w.w = pk2(v[6], v[7]); return w; }
;     DI void operator()(const f32x4 (&acc)[2][2][4][2], const pg8::Unit& u, int wr, int wc, int fr, int fq) const {
;     ...
;             for (int m = 0; m < 4; ++m) { const int row = row0 + ai * 128 + m * 16; const size_t off = (size_t)row * DMODEL + col0; float s = 0.f, q = 0.f;
; #pragma unroll
;                 for (int bj = 0; bj < 2; ++bj) { float r[8];
;                     if (res32) { const f32x4 r0 = *(const f32x4*)(res32 + off + bj * 128), r1 = *(const f32x4*)(res32 + off + bj * 128 + 4); r[0] = r0[0]; r[1] = r0[1]; r[2] = r0[2]; r[3] = r0[3]; r[4] = r1[0]; r[5] = r1[1]; r[6] = r1[2]; r[7] = r1[3]; }
;                     else unpack8(*(const u32x4*)(res16 + off + bj * 128), r);
;                     float o[8];
; #pragma unroll
;                     for (int k = 0; k < 8; ++k) { o[k] = r[k] * ALPHA + acc[ai][bj][m][k >> 2][k & 3]; s += o[k]; q += o[k] * o[k]; }
;                     *(u32x4*)(XBo + off + bj * 128) = pack8(o); }
.LBB0_1788:
	s_or_b64 exec, exec, s[2:3]
	v_add_u32_e32 v58, 0x90, v150
	v_ashrrev_i32_e32 v59, 31, v58
	v_lshlrev_b64 v[50:51], 10, v[58:59]
	v_lshl_add_u64 v[60:61], v[50:51], 0, v[148:149]
	s_and_b64 vcc, exec, s[18:19]
	v_lshl_add_u64 v[62:63], v[60:61], 2, s[26:27]
	s_cbranch_vccnz .LBB0_1824
	global_load_dwordx4 v[54:57], v[62:63], off
	s_waitcnt lgkmcnt(0)
	global_load_dwordx4 v[50:53], v[62:63], off offset:16
	global_load_dwordx4 v[164:167], v[62:63], off offset:528
	global_load_dwordx4 v[168:171], v[62:63], off offset:512
	v_lshl_add_u64 v[60:61], v[60:61], 1, s[24:25]
	s_cbranch_execnz .LBB0_1791
.LBB0_1790:
	s_waitcnt lgkmcnt(0)
	global_load_dwordx4 v[50:53], v[60:61], off
	global_load_dwordx4 v[172:175], v[60:61], off offset:256
	s_waitcnt vmcnt(0)
	v_lshlrev_b32_e32 v54, 16, v50
	v_and_b32_e32 v55, 0xffff0000, v50
	v_lshlrev_b32_e32 v56, 16, v51
	v_and_b32_e32 v57, 0xffff0000, v51
	v_lshlrev_b32_e32 v50, 16, v52
	v_and_b32_e32 v51, 0xffff0000, v52
	v_lshlrev_b32_e32 v52, 16, v53
	v_and_b32_e32 v53, 0xffff0000, v53
.LBB0_1791:
	s_waitcnt vmcnt(1)
	v_pk_fma_f32 v[54:55], v[54:55], s[86:87], v[46:47] op_sel_hi:[1,0,1]
	v_pk_fma_f32 v[56:57], v[56:57], s[86:87], v[48:49] op_sel_hi:[1,0,1]
	s_waitcnt vmcnt(0)
	v_pk_fma_f32 v[64:65], v[50:51], s[86:87], v[42:43] op_sel_hi:[1,0,1]
	s_waitcnt lgkmcnt(0)
	v_pk_fma_f32 v[52:53], v[52:53], s[86:87], v[44:45] op_sel_hi:[1,0,1]
	v_cvt_pk_bf16_f32 v42, v54, v55
	v_cvt_pk_bf16_f32 v43, v56, v57
	v_cvt_pk_bf16_f32 v44, v64, v65
	v_cvt_pk_bf16_f32 v45, v52, v53
	s_and_b64 vcc, exec, s[18:19]
	global_store_dwordx4 v[60:61], v[42:45], off
	s_cbranch_vccnz .LBB0_1825
	s_nop 2
	v_mov_b32_e32 v42, v164
	v_mov_b32_e32 v43, v165
	v_mov_b32_e32 v44, v166
	v_mov_b32_e32 v45, v167
	v_mov_b32_e32 v46, v168
	v_mov_b32_e32 v47, v169
	v_mov_b32_e32 v48, v170
	v_mov_b32_e32 v49, v171
	s_waitcnt vmcnt(1)
	v_mov_b32_e32 v50, v45
	s_cbranch_execnz .LBB0_1794
.LBB0_1793:
	s_nop 2
	v_mov_b32_e32 v42, v172
	v_mov_b32_e32 v43, v173
	v_mov_b32_e32 v44, v174
	v_mov_b32_e32 v45, v175
	s_waitcnt vmcnt(0)
	v_lshlrev_b32_e32 v46, 16, v42
	v_and_b32_e32 v47, 0xffff0000, v42
	v_lshlrev_b32_e32 v48, 16, v43
	v_and_b32_e32 v49, 0xffff0000, v43
	v_lshlrev_b32_e32 v42, 16, v44
	v_and_b32_e32 v43, 0xffff0000, v44
	v_lshlrev_b32_e32 v44, 16, v45
	v_and_b32_e32 v50, 0xffff0000, v45

; DI u32x4 pack8(const float (&v)[8]) { u32x4 w; w.x = pk2(v[0], v[1]); w.y = pk2(v[2], v[3]); w.z = pk2(v[4], v[5]); w.w = pk2(v[6], v[7]); return w; }
;     DI void operator()(const f32x4 (&acc)[2][2][4][2], const pg8::Unit& u, int wr, int wc, int fr, int fq) const {
;     ...
;             for (int m = 0; m < 4; ++m) { const int row = row0 + ai * 128 + m * 16; const size_t off = (size_t)row * DMODEL + col0; float s = 0.f, q = 0.f;
; #pragma unroll
;                 for (int bj = 0; bj < 2; ++bj) { float r[8];
;                     if (res32) { const f32x4 r0 = *(const f32x4*)(res32 + off + bj * 128), r1 = *(const f32x4*)(res32 + off + bj * 128 + 4); r[0] = r0[0]; r[1] = r0[1]; r[2] = r0[2]; r[3] = r0[3]; r[4] = r1[0]; r[5] = r1[1]; r[6] = r1[2]; r[7] = r1[3]; }
;                     else unpack8(*(const u32x4*)(res16 + off + bj * 128), r);
;                     float o[8];
; #pragma unroll
;                     for (int k = 0; k < 8; ++k) { o[k] = r[k] * ALPHA + acc[ai][bj][m][k >> 2][k & 3]; s += o[k]; q += o[k] * o[k]; }
;                     *(u32x4*)(XBo + off + bj * 128) = pack8(o); }
.LBB0_1796:
	s_or_b64 exec, exec, s[2:3]
	v_add_u32_e32 v42, 0xa0, v150
	v_ashrrev_i32_e32 v43, 31, v42
	v_lshlrev_b64 v[34:35], 10, v[42:43]
	v_lshl_add_u64 v[44:45], v[34:35], 0, v[148:149]
	s_and_b64 vcc, exec, s[18:19]
	v_lshl_add_u64 v[46:47], v[44:45], 2, s[26:27]
	s_cbranch_vccnz .LBB0_1826
	global_load_dwordx4 v[38:41], v[46:47], off
	s_waitcnt lgkmcnt(0)
	global_load_dwordx4 v[34:37], v[46:47], off offset:16
	global_load_dwordx4 v[164:167], v[46:47], off offset:528
	global_load_dwordx4 v[168:171], v[46:47], off offset:512
	v_lshl_add_u64 v[44:45], v[44:45], 1, s[24:25]
	s_cbranch_execnz .LBB0_1799
.LBB0_1798:
	s_waitcnt lgkmcnt(0)
	global_load_dwordx4 v[34:37], v[44:45], off
	global_load_dwordx4 v[172:175], v[44:45], off offset:256
	s_waitcnt vmcnt(0)
	v_lshlrev_b32_e32 v38, 16, v34
	v_and_b32_e32 v39, 0xffff0000, v34
	v_lshlrev_b32_e32 v40, 16, v35
	v_and_b32_e32 v41, 0xffff0000, v35
	v_lshlrev_b32_e32 v34, 16, v36
	v_and_b32_e32 v35, 0xffff0000, v36
	v_lshlrev_b32_e32 v36, 16, v37
	v_and_b32_e32 v37, 0xffff0000, v37
.LBB0_1799:
	s_waitcnt vmcnt(1)
	v_pk_fma_f32 v[38:39], v[38:39], s[86:87], v[30:31] op_sel_hi:[1,0,1]
	v_pk_fma_f32 v[40:41], v[40:41], s[86:87], v[32:33] op_sel_hi:[1,0,1]
	s_waitcnt vmcnt(0)
	v_pk_fma_f32 v[48:49], v[34:35], s[86:87], v[26:27] op_sel_hi:[1,0,1]
	s_waitcnt lgkmcnt(0)
	v_pk_fma_f32 v[36:37], v[36:37], s[86:87], v[28:29] op_sel_hi:[1,0,1]
	v_cvt_pk_bf16_f32 v26, v38, v39
	v_cvt_pk_bf16_f32 v27, v40, v41
	v_cvt_pk_bf16_f32 v28, v48, v49
	v_cvt_pk_bf16_f32 v29, v36, v37
	s_and_b64 vcc, exec, s[18:19]
	global_store_dwordx4 v[44:45], v[26:29], off
	s_cbranch_vccnz .LBB0_1827
	s_nop 2
	v_mov_b32_e32 v26, v164
	v_mov_b32_e32 v27, v165
	v_mov_b32_e32 v28, v166
	v_mov_b32_e32 v29, v167
	v_mov_b32_e32 v30, v168
	v_mov_b32_e32 v31, v169
	v_mov_b32_e32 v32, v170
	v_mov_b32_e32 v33, v171
	s_waitcnt vmcnt(1)
	v_mov_b32_e32 v34, v29
	s_cbranch_execnz .LBB0_1802
.LBB0_1801:
	s_nop 2
	v_mov_b32_e32 v26, v172
	v_mov_b32_e32 v27, v173
	v_mov_b32_e32 v28, v174
	v_mov_b32_e32 v29, v175
	s_waitcnt vmcnt(0)
	v_lshlrev_b32_e32 v30, 16, v26
	v_and_b32_e32 v31, 0xffff0000, v26
	v_lshlrev_b32_e32 v32, 16, v27
	v_and_b32_e32 v33, 0xffff0000, v27
	v_lshlrev_b32_e32 v26, 16, v28
	v_and_b32_e32 v27, 0xffff0000, v28
	v_lshlrev_b32_e32 v28, 16, v29
	v_and_b32_e32 v34, 0xffff0000, v29

; DI u32x4 pack8(const float (&v)[8]) { u32x4 w; w.x = pk2(v[0], v[1]); w.y = pk2(v[2], v[3]); w.z = pk2(v[4], v[5]); w.w = pk2(v[6], v[7]); return w; }
;     DI void operator()(const f32x4 (&acc)[2][2][4][2], const pg8::Unit& u, int wr, int wc, int fr, int fq) const {
;     ...
;             for (int m = 0; m < 4; ++m) { const int row = row0 + ai * 128 + m * 16; const size_t off = (size_t)row * DMODEL + col0; float s = 0.f, q = 0.f;
; #pragma unroll
;                 for (int bj = 0; bj < 2; ++bj) { float r[8];
;                     if (res32) { const f32x4 r0 = *(const f32x4*)(res32 + off + bj * 128), r1 = *(const f32x4*)(res32 + off + bj * 128 + 4); r[0] = r0[0]; r[1] = r0[1]; r[2] = r0[2]; r[3] = r0[3]; r[4] = r1[0]; r[5] = r1[1]; r[6] = r1[2]; r[7] = r1[3]; }
;                     else unpack8(*(const u32x4*)(res16 + off + bj * 128), r);
;                     float o[8];
; #pragma unroll
;                     for (int k = 0; k < 8; ++k) { o[k] = r[k] * ALPHA + acc[ai][bj][m][k >> 2][k & 3]; s += o[k]; q += o[k] * o[k]; }
;                     *(u32x4*)(XBo + off + bj * 128) = pack8(o); }
.LBB0_1804:
	s_or_b64 exec, exec, s[2:3]
	v_add_u32_e32 v26, 0xb0, v150
	v_ashrrev_i32_e32 v27, 31, v26
	v_lshlrev_b64 v[18:19], 10, v[26:27]
	v_lshl_add_u64 v[28:29], v[18:19], 0, v[148:149]
	s_and_b64 vcc, exec, s[18:19]
	v_lshl_add_u64 v[30:31], v[28:29], 2, s[26:27]
	s_cbranch_vccnz .LBB0_1828
	global_load_dwordx4 v[22:25], v[30:31], off
	s_waitcnt lgkmcnt(0)
	global_load_dwordx4 v[18:21], v[30:31], off offset:16
	global_load_dwordx4 v[164:167], v[30:31], off offset:528
	global_load_dwordx4 v[168:171], v[30:31], off offset:512
	v_lshl_add_u64 v[28:29], v[28:29], 1, s[24:25]
	s_cbranch_execnz .LBB0_1807
.LBB0_1806:
	s_waitcnt lgkmcnt(0)
	global_load_dwordx4 v[18:21], v[28:29], off
	global_load_dwordx4 v[172:175], v[28:29], off offset:256
	s_waitcnt vmcnt(0)
	v_lshlrev_b32_e32 v22, 16, v18
	v_and_b32_e32 v23, 0xffff0000, v18
	v_lshlrev_b32_e32 v24, 16, v19
	v_and_b32_e32 v25, 0xffff0000, v19
	v_lshlrev_b32_e32 v18, 16, v20
	v_and_b32_e32 v19, 0xffff0000, v20
	v_lshlrev_b32_e32 v20, 16, v21
	v_and_b32_e32 v21, 0xffff0000, v21
.LBB0_1807:
	s_waitcnt vmcnt(1)
	v_pk_fma_f32 v[22:23], v[22:23], s[86:87], v[14:15] op_sel_hi:[1,0,1]
	v_pk_fma_f32 v[24:25], v[24:25], s[86:87], v[16:17] op_sel_hi:[1,0,1]
	s_waitcnt vmcnt(0)
	v_pk_fma_f32 v[32:33], v[18:19], s[86:87], v[10:11] op_sel_hi:[1,0,1]
	s_waitcnt lgkmcnt(0)
	v_pk_fma_f32 v[20:21], v[20:21], s[86:87], v[12:13] op_sel_hi:[1,0,1]
	v_cvt_pk_bf16_f32 v10, v22, v23
	v_cvt_pk_bf16_f32 v11, v24, v25
	v_cvt_pk_bf16_f32 v12, v32, v33
	v_cvt_pk_bf16_f32 v13, v20, v21
	s_and_b64 vcc, exec, s[18:19]
	global_store_dwordx4 v[28:29], v[10:13], off
	s_cbranch_vccnz .LBB0_1829
	s_nop 2
	v_mov_b32_e32 v10, v164
	v_mov_b32_e32 v11, v165
	v_mov_b32_e32 v12, v166
	v_mov_b32_e32 v13, v167
	v_mov_b32_e32 v14, v168
	v_mov_b32_e32 v15, v169
	v_mov_b32_e32 v16, v170
	v_mov_b32_e32 v17, v171
	s_waitcnt vmcnt(1)
	v_mov_b32_e32 v18, v13
	s_cbranch_execnz .LBB0_1810
.LBB0_1809:
	s_nop 2
	v_mov_b32_e32 v10, v172
	v_mov_b32_e32 v11, v173
	v_mov_b32_e32 v12, v174
	v_mov_b32_e32 v13, v175
	s_waitcnt vmcnt(0)
	v_lshlrev_b32_e32 v14, 16, v10
	v_and_b32_e32 v15, 0xffff0000, v10
	v_lshlrev_b32_e32 v16, 16, v11
	v_and_b32_e32 v17, 0xffff0000, v11
	v_lshlrev_b32_e32 v10, 16, v12
	v_and_b32_e32 v11, 0xffff0000, v12
	v_lshlrev_b32_e32 v12, 16, v13
	v_and_b32_e32 v18, 0xffff0000, v13
